# v047 with the static P3 priority raise given to waves 4-7 instead of waves 0-3
# speedup vs baseline: 1.0115x; 1.0115x over previous
; __device__ __forceinline__ void xcd_barrier(unsigned* bar, volatile LAS unsigned* st, bool leader, unsigned G) {
;     ...
;     __syncthreads();
; __global__ void __launch_bounds__(512, 2) hybrid_fwd(Params p) {
;     ...
;         if (PH(3)) { PHB
;             if (c < 128) {
;                 const int u = c;
;                     const int qb = 31 - (u >> 2), hd = u & 3, tq0 = 256 * qb + 32 * wave, t_row = tq0 + (lane & 31);
.LBB0_533:
	s_or_b64 exec, exec, s[0:1]
	v_readlane_b32 s0, v255, 0
	s_mov_b32 s70, s23
	s_mov_b32 s2, s0
	v_mov_b32_e32 v144, v234
	s_waitcnt lgkmcnt(0)
	s_barrier
	s_mov_b64 s[8:9], s[50:51]
	v_readfirstlane_b32 s15, v144
	s_ashr_i32 s3, s15, 6
	s_cmp_ge_u32 s3, 4
	s_cbranch_scc0 .Lp3_prio_skip
	s_setprio 2
